# v20 plus prologue load hoist in the remaining GEMM phase (HGRN projections)
# speedup vs baseline: 1.0007x; 1.0007x over previous
; #define PG8_STAGE(bufoff, gbase, voff) do { _Pragma("unroll") for (int _i = 0; _i < 2; ++_i) \
;         __builtin_amdgcn_global_load_lds((const unsigned*)((const char*)(gbase) + (voff)[_i]), (PG8_LAS unsigned*)(lds + (bufoff) + ldsw + _i * 8192), 16, 0, 0); } while (0)
; #define PG8_WAIT_V(n) asm volatile("s_waitcnt vmcnt(" #n ")" ::: "memory")
; #define PG8_BAR __builtin_amdgcn_s_barrier()
; template <class Epi, class Sched, bool ALIGN_EPI = false, bool SP2 = false>
; __device__ __forceinline__ void gemm_phase(PG8_LAS unsigned char* lds, const Gemm g, const Sched& S, const Epi& E) {
;     ...
;     const unsigned ldsw = (unsigned)wid * 1024u;
;     const int aoff = lds_byte(wr * 64 + fr, fq * 8), boff = lds_byte(wc * 32 + fr, fq * 8);
;     ...
;         PG8_STAGE(PG8_SB(0, 0), cB, voffB); PG8_STAGE(PG8_SB(0, 1), cB + hstep, voffB); PG8_STAGE(PG8_SA(0, 0), cA, voffA); PG8_STAGE(PG8_SA(0, 1), cA + hstep, voffA);
;         if (wr == 1) PG8_BAR;
;         PG8_WAIT_V(2); PG8_BAR;
;         PG8_STAGE(PG8_SB(1, 0), cB + kstep, voffB); PG8_STAGE(PG8_SA(1, 0), cA + kstep, voffA); PG8_STAGE(PG8_SB(1, 1), cB + hstep + kstep, voffB);
;         PG8_WAIT_V(6); PG8_BAR;
.LBB0_599:
	s_lshl_b32 s4, s4, 5
	s_mov_b64 s[16:17], 0x80
	s_and_b32 s7, s4, 0x60
	s_add_i32 m0, s43, 0x18000
	v_lshl_add_u64 v[6:7], v[6:7], 0, s[16:17]
	s_lshl_b32 s1, s3, 13
	s_lshl_b32 s18, s7, 7
	global_load_lds_dwordx4 v[6:7], off
	v_lshl_add_u64 v[2:3], v[2:3], 0, s[16:17]
	s_add_i32 m0, s43, 0x1a000
	s_add_i32 s48, s43, 0x8000
	s_add_i32 s49, s43, 0xa000
	global_load_lds_dwordx4 v[2:3], off
	v_lshl_add_u64 v[0:1], v[0:1], 0, s[16:17]
	s_mov_b32 m0, s48
	s_add_u32 s4, s38, 0x80080
	global_load_lds_dwordx4 v[0:1], off
	v_lshl_add_u64 v[0:1], v[4:5], 0, s[16:17]
	s_mov_b32 m0, s49
	s_addc_u32 s5, s39, 0
	global_load_lds_dwordx4 v[0:1], off
	s_add_i32 m0, s43, 0x1c000
	v_lshl_add_u64 v[0:1], s[4:5], 0, v[138:139]
	global_load_lds_dwordx4 v[0:1], off
	v_lshl_add_u64 v[0:1], s[4:5], 0, v[142:143]
	s_add_i32 m0, s43, 0x1e000
	s_cmpk_lt_u32 s2, 0x100
	global_load_lds_dwordx4 v[0:1], off
	v_lshrrev_b32_e32 v1, 1, v8
	v_and_b32_e32 v1, 24, v1
	v_and_b32_e32 v0, 15, v8
	v_lshlrev_b32_e32 v2, 1, v1
	s_waitcnt vmcnt(0)
	v_lshl_or_b32 v160, s3, 6, v0
	v_lshl_or_b32 v0, v0, 6, v2
	v_lshlrev_b32_e32 v2, 2, v8
	v_and_b32_e32 v2, 32, v2
	v_bitop3_b32 v3, v0, s1, v2 bitop3:0xde
	v_bitop3_b32 v161, v0, s18, v2 bitop3:0xde
	v_lshlrev_b32_e32 v0, 15, v9
	v_and_b32_e32 v0, 0xffff0000, v0
	v_or_b32_e32 v162, s7, v1
	v_lshl_add_u32 v0, v10, 12, v0
	v_and_b32_e32 v1, 1, v9
	v_lshl_or_b32 v0, v1, 6, v0
	v_lshl_add_u32 v146, v11, 1, v0
	v_lshlrev_b32_e32 v0, 15, v12
	v_and_b32_e32 v0, 0xffff0000, v0
	s_waitcnt vmcnt(8)
	s_barrier
	s_waitcnt vmcnt(6)
	v_lshl_add_u32 v0, v13, 12, v0
	v_and_b32_e32 v1, 1, v12
	s_cselect_b64 s[18:19], -1, 0
	v_lshl_or_b32 v0, v1, 6, v0
	s_add_i32 s53, 0, 0x10000
	s_add_i32 s54, 0, 0x14000
	s_ashr_i32 s50, s76, 31
	s_mov_b32 s51, s76
	s_ashr_i32 s52, s74, 31
	v_mov_b32_e32 v147, v145
	v_lshl_add_u32 v148, v14, 1, v0
	v_mov_b32_e32 v149, v145
	v_mov_b64_e32 v[150:151], 0x600
	v_mov_b64_e32 v[152:153], 0x5ff
	v_add_u32_e32 v163, s53, v161
	v_add_u32_e32 v164, s54, v161
	v_add_u32_e32 v165, 0, v3
	s_mov_b64 s[20:21], 0x90000
	s_mov_b64 s[22:23], 0xa0000
	s_mov_b64 s[24:25], 0xb0000
	s_mov_b32 s55, 0x800000
	s_mov_b32 s56, 0x3f317217
	s_mov_b32 s57, 0x7f800000
	v_mov_b32_e32 v166, 0x41b17218
	s_barrier
	s_branch .LBB0_602
